# grid barrier: L1/L2 invalidate moved ahead of the wait (no loads between arrival and release), census loads batched; plus slack copy
# speedup vs baseline: 1.0132x; 1.0132x over previous
.LBB0_1100:
	v_readlane_b32 s8, v252, 26
	v_readlane_b32 s9, v252, 27
	v_readlane_b32 s10, v253, 49
	s_nop 3
	global_load_dword v0, v1, s[8:9] sc1
	v_readlane_b32 s8, v252, 28
	v_readlane_b32 s9, v252, 29
	s_waitcnt lgkmcnt(0)
	s_nop 3
	global_load_dword v2, v1, s[8:9] sc1
	v_readlane_b32 s8, v252, 30
	v_readlane_b32 s9, v252, 31
	s_nop 1
	s_nop 2
	global_load_dword v3, v1, s[8:9] sc1
	v_readlane_b32 s8, v252, 32
	v_readlane_b32 s9, v252, 33
	s_nop 1
	s_nop 2
	global_load_dword v4, v1, s[8:9] sc1
	v_readlane_b32 s8, v252, 34
	v_readlane_b32 s9, v252, 35
	s_nop 1
	s_nop 2
	global_load_dword v5, v1, s[8:9] sc1
	v_readlane_b32 s8, v252, 36
	v_readlane_b32 s9, v252, 37
	s_nop 1
	s_nop 2
	global_load_dword v6, v1, s[8:9] sc1
	v_readlane_b32 s8, v252, 38
	v_readlane_b32 s9, v252, 39
	s_nop 1
	s_nop 2
	global_load_dword v7, v1, s[8:9] sc1
	v_readlane_b32 s8, v252, 40
	v_readlane_b32 s9, v252, 41
	s_nop 1
	s_nop 2
	global_load_dword v8, v1, s[8:9] sc1
	v_readlane_b32 s8, v252, 42
	v_readlane_b32 s9, v252, 43
	s_nop 1
	s_nop 2
	global_load_dword v9, v1, s[8:9] sc1
	v_readlane_b32 s8, v252, 44
	v_readlane_b32 s9, v252, 45
	s_nop 1
	s_nop 2
	global_load_dword v10, v1, s[8:9] sc1
	v_readlane_b32 s8, v252, 46
	v_readlane_b32 s9, v252, 47
	s_nop 1
	s_nop 2
	global_load_dword v11, v1, s[8:9] sc1
	v_readlane_b32 s8, v252, 48
	v_readlane_b32 s9, v252, 49
	s_nop 1
	s_nop 2
	global_load_dword v12, v1, s[8:9] sc1
	v_readlane_b32 s8, v252, 50
	v_readlane_b32 s9, v252, 51
	s_nop 1
	s_nop 2
	global_load_dword v13, v1, s[8:9] sc1
	v_readlane_b32 s8, v252, 52
	v_readlane_b32 s9, v252, 53
	s_nop 1
	s_nop 2
	global_load_dword v14, v1, s[8:9] sc1
	v_readlane_b32 s8, v252, 54
	v_readlane_b32 s9, v252, 55
	s_nop 1
	s_nop 2
	global_load_dword v15, v1, s[8:9] sc1
	v_readlane_b32 s8, v252, 56
	v_readlane_b32 s9, v252, 57
	s_nop 1
	s_nop 2
	global_load_dword v16, v1, s[8:9] sc1
	s_mov_b64 s[8:9], -1
	s_waitcnt vmcnt(0)
	v_add_u32_e32 v17, v2, v0
	v_add_u32_e32 v17, v17, v3
	v_add_u32_e32 v17, v17, v4
	v_add_u32_e32 v17, v17, v5
	v_add_u32_e32 v17, v17, v6
	v_add_u32_e32 v17, v17, v7
	v_add_u32_e32 v17, v17, v8
	v_add_u32_e32 v17, v17, v9
	v_add_u32_e32 v17, v17, v10
	v_add_u32_e32 v17, v17, v11
	v_add_u32_e32 v17, v17, v12
	v_add_u32_e32 v17, v17, v13
	v_add_u32_e32 v17, v17, v14
	v_add_u32_e32 v17, v17, v15
	v_add_u32_e32 v17, v17, v16
	v_cmp_eq_u32_e32 vcc, s10, v17
	s_mov_b64 s[10:11], -1
	s_cbranch_vccnz .LBB0_1099
	s_and_b32 s8, s14, 0xff
	s_cmp_eq_u32 s8, 0
	s_mov_b64 s[8:9], -1
	s_mov_b64 s[12:13], -1
	s_sleep 1
	s_cbranch_scc0 .LBB0_1104
	v_readlane_b32 s8, v252, 24
	v_readlane_b32 s9, v252, 25
	s_nop 4
	global_load_dword v17, v1, s[8:9] sc1
	s_waitcnt vmcnt(0)
	v_cmp_eq_u32_e32 vcc, 0, v17
	s_cbranch_vccnz .LBB0_1106
	s_mov_b64 s[12:13], 0
	s_mov_b64 s[8:9], -1

.LBB0_1114:
	s_or_b64 exec, exec, s[8:9]
	v_cvt_f32_u32_e32 v5, v3
	s_waitcnt vmcnt(0)
	v_readfirstlane_b32 s8, v4
	v_sub_u32_e32 v4, 0, v3
	v_rcp_iflag_f32_e32 v5, v5
	v_add_u32_e32 v6, s8, v0
	v_mul_f32_e32 v5, 0x4f7ffffe, v5
	v_cvt_u32_f32_e32 v5, v5
	v_mul_lo_u32 v0, v4, v5
	v_mul_hi_u32 v0, v5, v0
	v_add_u32_e32 v0, v5, v0
	v_mul_hi_u32 v0, v6, v0
	v_mul_lo_u32 v4, v0, v3
	v_sub_u32_e32 v4, v6, v4
	v_add_u32_e32 v5, 1, v0
	v_cmp_ge_u32_e32 vcc, v4, v3
	s_nop 1
	v_cndmask_b32_e32 v0, v0, v5, vcc
	v_sub_u32_e32 v5, v4, v3
	v_cndmask_b32_e32 v4, v4, v5, vcc
	v_add_u32_e32 v5, 1, v0
	v_cmp_ge_u32_e32 vcc, v4, v3
	v_add_u32_e32 v4, 1, v6
	s_nop 0
	v_cndmask_b32_e32 v0, v0, v5, vcc
	v_mul_lo_u32 v5, v3, v0
	v_add_u32_e32 v3, v5, v3
	v_cmp_ne_u32_e32 vcc, v4, v3
	s_and_saveexec_b64 s[8:9], vcc
	s_xor_b64 s[8:9], exec, s[8:9]
	s_cbranch_execz .LBB0_1128
	v_readlane_b32 s10, v253, 28
	v_readlane_b32 s11, v253, 29
	s_waitcnt lgkmcnt(0)
	s_nop 3
	buffer_inv sc1
	global_load_dword v2, v1, s[10:11] sc1
	s_waitcnt vmcnt(0)
	v_cmp_eq_u32_e32 vcc, v2, v0
	s_and_saveexec_b64 s[10:11], vcc
	s_cbranch_execz .LBB0_1127
	s_mov_b32 s24, 1
	s_mov_b64 s[12:13], 0
	s_branch .LBB0_1118

.LBB0_1127:
	s_or_b64 exec, exec, s[10:11]
	s_waitcnt vmcnt(0)
	s_waitcnt vmcnt(0)
.LBB0_1128:
	s_andn2_saveexec_b64 s[8:9], s[8:9]
	s_cbranch_execz .LBB0_1148
	s_mov_b64 s[8:9], exec
	buffer_wbl2 sc1
	s_waitcnt lgkmcnt(0)
	s_waitcnt vmcnt(0)
	buffer_inv sc1
	v_mbcnt_lo_u32_b32 v0, s8, 0
	v_mbcnt_hi_u32_b32 v0, s9, v0
	v_cmp_eq_u32_e32 vcc, 0, v0
	s_and_saveexec_b64 s[10:11], vcc
	s_cbranch_execz .LBB0_1131
	s_bcnt1_i32_b64 s8, s[8:9]
	v_mov_b32_e32 v3, s8
	v_readlane_b32 s8, v253, 30
	v_readlane_b32 s9, v253, 31
	s_nop 4
	global_atomic_add v3, v1, v3, s[8:9] sc0

.LBB0_1145:
	s_or_b64 exec, exec, s[8:9]
	s_mov_b64 s[8:9], exec
	v_mbcnt_lo_u32_b32 v0, s8, 0
	v_mbcnt_hi_u32_b32 v0, s9, v0
	v_cmp_eq_u32_e32 vcc, 0, v0
	s_waitcnt vmcnt(0)
	s_and_saveexec_b64 s[10:11], vcc
	s_cbranch_execz .LBB0_1147
	s_bcnt1_i32_b64 s8, s[8:9]
	v_mov_b32_e32 v0, s8
	v_readlane_b32 s8, v253, 28
	v_readlane_b32 s9, v253, 29
	s_nop 4
	global_atomic_add v1, v0, s[8:9]
